# attention prompt-unit prologue: rotary table rows requested with the Q tile (set 1) / under the Q-nope norm (set 2) instead of two load-then-wait points
# baseline (speedup 1.0000x reference)
; template <int VAR>
; __device__ __forceinline__ void attn_unit(const AUnit& u, LAS char* lds) {
;     ...
;     const int tid = tid_, wid = __builtin_amdgcn_readfirstlane(tid >> 6), lane = tid & 63, r32 = lane & 31, hi = lane >> 5;
;     const bool wact = wid < u.nwav;
;     const int jmax = u.jbase + (wid >> 1);
;     const bf16_t* gk0; const bf16_t* gk1; const bf16_t* gkr; const bf16_t* gv0; const bf16_t* gv1;
;     {
;         const int rk0 = (2 * wid) * 4 + (lane >> 4), rk1 = rk0 + 4, ph = lane & 15;
;         gk0 = u.Kn + (size_t)rk0 * 128 + ((ph ^ (rk0 & 15)) * 8);
;         gk1 = u.Kn + (size_t)rk1 * 128 + ((ph ^ (rk1 & 15)) * 8);
;         const int rr0 = wid * 8 + (lane >> 3), pr = lane & 7;
;         gkr = u.Kr + (size_t)rr0 * ROPE + ((pr ^ ((rr0 >> 1) & 7)) * 8);
; #pragma unroll
;         for (int i = 0; i < 2; ++i) {
;             const int st = (2 * wid + i) * 2 + (lane >> 5), o16 = lane & 31, kk = (st >> 2) * 8 + (o16 >> 2), c = (st & 3) * 32 + (o16 & 3) * 8;
;             const int key = (kk & ~0xC) | ((kk & 4) << 1) | ((kk & 8) >> 1);
;             const bf16_t* p = u.V + (size_t)key * 128 + c;
;             if (i == 0) gv0 = p; else gv1 = p;
;         }
;     }
;     ...
;     ADMA(0, 0);
;     bf16x8 qr[12];
;     {
;         const int wq = wact ? wid : 0;
;         const bf16_t* qp = u.Q + (size_t)(wq * 32 + r32) * QW + hi * 8;
; #pragma unroll
;         for (int d0 = 0; d0 < 12; ++d0) qr[d0] = *(const bf16x8*)(qp + d0 * 16);
;     ...
;         const int pos = u.pos0 + wq * 32 + r32;
; #pragma unroll
;         for (int a = 0; a < 2; ++a) { float x1[8], x2[8]; unpack8(__builtin_bit_cast(u32x4, qr[8 + a]), x1); unpack8(__builtin_bit_cast(u32x4, qr[10 + a]), x2);
;             const int i0 = a * 16 + hi * 8;
;             const f32x4 ga0 = *(const f32x4*)(u.gqr + i0), ga1 = *(const f32x4*)(u.gqr + i0 + 4), gb0 = *(const f32x4*)(u.gqr + 32 + i0), gb1 = *(const f32x4*)(u.gqr + 32 + i0 + 4);
;             float y1[8], y2[8];
; #pragma unroll
;             for (int e = 0; e < 8; ++e) { const float v1 = x1[e] * rr_ * (e < 4 ? ga0[e & 3] : ga1[e & 3]), v2 = x2[e] * rr_ * (e < 4 ? gb0[e & 3] : gb1[e & 3]);
;                 const float2 cs = u.tab[pos * 32 + i0 + e];
.LBB0_941:
	s_lshl_b64 s[2:3], s[10:11], 8
	s_add_u32 s54, s2, s40
	s_addc_u32 s55, s3, s41
	s_mul_i32 s2, s55, 0x1800
	s_mul_hi_u32 s3, s54, 0x1800
	s_add_i32 s3, s3, s2
	s_mul_i32 s2, s54, 0x1800
	v_mov_b32_e32 v181, v0
	s_add_u32 s2, s76, s2
	s_addc_u32 s3, s77, s3
	v_readfirstlane_b32 s5, v181
	s_ashr_i32 s19, s5, 6
	s_lshl_b32 s56, s19, 3
	s_waitcnt lgkmcnt(0)
	v_bfe_u32 v2, v181, 4, 2
	s_waitcnt vmcnt(0)
	v_or_b32_e32 v4, s56, v2
	v_and_b32_e32 v2, 15, v181
	v_ashrrev_i32_e32 v5, 31, v4
	v_bitop3_b32 v10, v4, v2, 11 bitop3:0x6c
	v_bfe_u32 v2, v181, 3, 3
	v_or_b32_e32 v32, 4, v4
	v_lshlrev_b64 v[36:37], 8, v[4:5]
	v_bitop3_b32 v12, v4, v181, 4 bitop3:0x36
	v_or_b32_e32 v4, s56, v2
	v_ashrrev_i32_e32 v33, 31, v32
	v_ashrrev_i32_e32 v5, 31, v4
	v_bfe_u32 v2, v181, 2, 3
	v_lshlrev_b64 v[34:35], 8, v[32:33]
	v_lshlrev_b64 v[38:39], 7, v[4:5]
	v_lshrrev_b32_e32 v33, 1, v4
	v_bitop3_b32 v2, s56, -13, v2 bitop3:0xc8
	v_lshrrev_b32_e32 v4, 1, v181
	s_lshl_b32 s56, s19, 2
	v_and_b32_e32 v4, 8, v4
	s_and_b32 s56, s56, 4
	v_or3_b32 v4, v2, v4, s56
	s_lshl_b32 s56, s19, 11
	s_add_i32 s84, s56, 0
	s_lshl_b32 s56, s19, 10
	s_lshl_b32 s4, s10, 2
	s_add_i32 s87, s56, 0
	s_add_i32 s57, s4, 4
	s_ashr_i32 s91, s5, 7
	v_xor_b32_e32 v14, v33, v181
	s_add_i32 s85, s84, 0x8000
	s_add_i32 s86, s84, 0x8400
	s_add_i32 s88, s87, 0xc000
	s_add_i32 s89, s84, 0x400
	s_lshl_b32 s56, s19, 5
	v_lshl_add_u64 v[8:9], s[42:43], 0, v[36:37]
	v_lshlrev_b32_e32 v42, 4, v10
	v_mov_b32_e32 v43, v3
	v_lshlrev_b32_e32 v12, 4, v12
	v_and_b32_e32 v90, 32, v181
	v_lshrrev_b32_e32 v248, 6, v181
	v_lshl_add_u32 v248, v248, 10, v90
	v_add_u32_e32 v248, 0x15000, v248
	v_lshlrev_b32_e32 v89, 3, v181
	v_ashrrev_i32_e32 v5, 31, v4
	s_cmp_lt_i32 s19, 8
	v_lshl_add_u64 v[8:9], v[8:9], 0, v[42:43]
	v_lshl_add_u64 v[10:11], s[42:43], 0, v[34:35]
	v_and_b32_e32 v12, 0xf0, v12
	v_mov_b32_e32 v13, v3
	v_lshlrev_b32_e32 v14, 4, v14
	s_mov_b32 m0, s85
	v_and_or_b32 v6, v89, 24, v90
	v_lshlrev_b64 v[40:41], 8, v[4:5]
	s_cselect_b64 s[58:59], -1, 0
	v_lshl_add_u64 v[10:11], v[10:11], 0, v[12:13]
	v_lshl_add_u64 v[12:13], s[48:49], 0, v[38:39]
	v_and_b32_e32 v14, 0x70, v14
	v_mov_b32_e32 v15, v3
	global_load_lds_dwordx4 v[8:9], off
	s_mov_b32 m0, s86
	v_lshl_add_u64 v[4:5], s[46:47], 0, v[40:41]
	v_lshlrev_b32_e32 v2, 1, v6
	v_lshl_add_u64 v[12:13], v[12:13], 0, v[14:15]
	global_load_lds_dwordx4 v[10:11], off
	s_mov_b32 m0, s88
	s_and_b64 s[60:61], s[58:59], exec
	v_and_b32_e32 v180, 31, v181
	v_lshl_add_u64 v[4:5], v[4:5], 0, v[2:3]
	global_load_lds_dwordx4 v[12:13], off
	s_mov_b32 m0, s84
	s_cselect_b32 s60, s56, 0
	v_lshl_add_u64 v[6:7], v[4:5], 0, s[28:29]
	v_bfe_u32 v182, v181, 5, 1
	global_load_lds_dwordx4 v[4:5], off
	v_or_b32_e32 v43, s60, v180
	v_mov_b64_e32 v[4:5], s[2:3]
	s_mov_b32 m0, s89
	v_mad_i64_i32 v[4:5], s[2:3], v43, s45, v[4:5]
	v_lshlrev_b32_e32 v162, 4, v182
	v_mov_b32_e32 v163, v3
	global_load_lds_dwordx4 v[6:7], off
	v_lshl_add_u64 v[8:9], v[4:5], 0, v[162:163]
	global_load_dwordx4 v[28:31], v[8:9], off
	global_load_dwordx4 v[24:27], v[8:9], off offset:32
	global_load_dwordx4 v[20:23], v[8:9], off offset:64
	global_load_dwordx4 v[44:47], v[8:9], off offset:96
	global_load_dwordx4 v[48:51], v[8:9], off offset:128
	global_load_dwordx4 v[52:55], v[8:9], off offset:160
	global_load_dwordx4 v[108:111], v[8:9], off offset:192
	global_load_dwordx4 v[112:115], v[8:9], off offset:224
	global_load_dwordx4 v[12:15], v[8:9], off offset:256
	global_load_dwordx4 v[4:7], v[8:9], off offset:288
	global_load_dwordx4 v[16:19], v[8:9], off offset:320
	s_nop 0
	global_load_dwordx4 v[8:11], v[8:9], off offset:352
	s_lshl_b32 s2, s10, 13
	v_lshl_add_u32 v43, v43, 5, s2
	v_and_b32_e32 v88, 63, v181
	v_lshl_add_u32 v183, v180, 8, 0
	s_add_i32 s10, 0, 0x12000
	s_and_b32 s2, s5, 0x3fffffc0
	s_lshl_b32 s2, s2, 2
	s_add_i32 s90, s2, 0
	v_or_b32_e32 v36, v36, v42
	v_or_b32_e32 v40, v40, v2
	s_add_i32 s90, s90, 0x14000
	v_lshl_add_u64 v[172:173], s[50:51], 0, v[36:37]
	v_lshl_add_u64 v[178:179], s[50:51], 0, v[40:41]
	v_mov_b32_e32 v2, v3
	s_mov_b32 s19, 0
	s_add_i32 s91, s91, s4
	v_bitop3_b32 v212, v162, v89, s21 bitop3:0x78
	v_cmp_gt_u32_e64 s[2:3], 32, v88
	v_lshl_add_u32 v206, v180, 2, s90
	v_mov_b32_e32 v225, 0
	v_mov_b32_e32 v226, 0xf149f2ca
	v_lshl_or_b32 v164, v182, 3, v43
	v_ashrrev_i32_e32 v165, 31, v164
	v_lshl_add_u64 v[194:195], v[164:165], 3, s[6:7]
	global_load_dwordx4 v[228:231], v[194:195], off offset:48
	global_load_dwordx4 v[232:235], v[194:195], off offset:32
	global_load_dwordx4 v[240:243], v[194:195], off offset:16
	global_load_dwordx4 v[244:247], v[194:195], off
	s_waitcnt vmcnt(0)
; __device__ __forceinline__ u32x4 pack8(const float* f) { u32x4 w; w.x = cvtpk(f[0], f[1]); w.y = cvtpk(f[2], f[3]); w.z = cvtpk(f[4], f[5]); w.w = cvtpk(f[6], f[7]); return w; }
; __device__ __forceinline__ bf16x8 pack8(const f32x4& a, const f32x4& b) { u32x4 w; w.x = cpk(a.x, a.y); w.y = cpk(a.z, a.w); w.z = cpk(b.x, b.y); w.w = cpk(b.z, b.w); return __builtin_bit_cast(bf16x8, w); }
; template <int VAR>
; __device__ __forceinline__ void attn_unit(const AUnit& u, LAS char* lds) {
;     ...
;         float ssn = 0.f, ssr = 0.f;
; #pragma unroll
;         for (int d0 = 0; d0 < 12; ++d0) { float f[8]; unpack8(__builtin_bit_cast(u32x4, qr[d0]), f); float a = 0.f;
; #pragma unroll
;             for (int e = 0; e < 8; ++e) a += f[e] * f[e];
;             if (d0 < 8) ssn += a; else ssr += a; }
;         { auto rr = __builtin_amdgcn_permlane32_swap(__float_as_uint(ssn), __float_as_uint(ssn), false, false); ssn = __uint_as_float(rr[0]) + __uint_as_float(rr[1]); }
;         { auto rr = __builtin_amdgcn_permlane32_swap(__float_as_uint(ssr), __float_as_uint(ssr), false, false); ssr = __uint_as_float(rr[0]) + __uint_as_float(rr[1]); }
;         const float rn = rsqrtf(ssn * (1.f / 128) + NORM_EPS) * QSCALE, rr_ = rsqrtf(ssr * (1.f / ROPE) + NORM_EPS);
; #pragma unroll
;         for (int d0 = 0; d0 < 8; ++d0) { float f[8]; unpack8(__builtin_bit_cast(u32x4, qr[d0]), f);
;             const f32x4 g0 = *(const f32x4*)(u.gqn + d0 * 16 + hi * 8), g1 = *(const f32x4*)(u.gqn + d0 * 16 + hi * 8 + 4);
; #pragma unroll
;             for (int e = 0; e < 4; ++e) { f[e] *= rn * g0[e]; f[4 + e] *= rn * g1[e]; }
;             qr[d0] = __builtin_bit_cast(bf16x8, pack8(f)); }
	v_and_b32_e32 v104, 0xffff0000, v28
	v_and_b32_e32 v96, 0xffff0000, v24
	v_lshlrev_b32_e32 v106, 16, v28
	v_mul_f32_e32 v28, v104, v104
	v_lshlrev_b32_e32 v100, 16, v24
	v_mul_f32_e32 v24, v96, v96
	v_and_b32_e32 v79, 0xffff0000, v44
	v_and_b32_e32 v78, 0xffff0000, v20
	v_lshlrev_b32_e32 v101, 16, v29
	v_fmac_f32_e32 v28, v106, v106
	v_lshlrev_b32_e32 v94, 16, v25
	v_fmac_f32_e32 v24, v100, v100
	v_lshlrev_b32_e32 v83, 16, v44
	v_lshlrev_b32_e32 v82, 16, v20
	v_lshlrev_b32_e32 v76, 16, v21
	v_and_b32_e32 v74, 0xffff0000, v21
	v_pk_mul_f32 v[20:21], v[78:79], v[78:79]
	v_and_b32_e32 v97, 0xffff0000, v29
	v_fmac_f32_e32 v28, v101, v101
	v_and_b32_e32 v92, 0xffff0000, v25
	v_fmac_f32_e32 v24, v94, v94
	v_lshlrev_b32_e32 v77, 16, v45
	v_pk_fma_f32 v[20:21], v[82:83], v[82:83], v[20:21]
	v_lshlrev_b32_e32 v107, 16, v30
	v_fmac_f32_e32 v28, v97, v97
	v_lshlrev_b32_e32 v102, 16, v26
	v_fmac_f32_e32 v24, v92, v92
	v_and_b32_e32 v75, 0xffff0000, v45
	v_pk_fma_f32 v[20:21], v[76:77], v[76:77], v[20:21]
	v_and_b32_e32 v105, 0xffff0000, v30
	v_fmac_f32_e32 v28, v107, v107
	v_and_b32_e32 v98, 0xffff0000, v26
	v_fmac_f32_e32 v24, v102, v102
	v_lshlrev_b32_e32 v87, 16, v46
	v_lshlrev_b32_e32 v86, 16, v22
	v_pk_fma_f32 v[20:21], v[74:75], v[74:75], v[20:21]
	v_lshlrev_b32_e32 v103, 16, v31
	v_fmac_f32_e32 v28, v105, v105
	v_lshlrev_b32_e32 v95, 16, v27
	v_fmac_f32_e32 v24, v98, v98
	v_and_b32_e32 v85, 0xffff0000, v46
	v_and_b32_e32 v84, 0xffff0000, v22
	v_pk_fma_f32 v[20:21], v[86:87], v[86:87], v[20:21]
	v_and_b32_e32 v99, 0xffff0000, v31
	v_fmac_f32_e32 v28, v103, v103
	v_and_b32_e32 v93, 0xffff0000, v27
	v_fmac_f32_e32 v24, v95, v95
	v_lshlrev_b32_e32 v81, 16, v47
	v_lshlrev_b32_e32 v80, 16, v23
	v_pk_fma_f32 v[20:21], v[84:85], v[84:85], v[20:21]
	v_fmac_f32_e32 v28, v99, v99
	v_fmac_f32_e32 v24, v93, v93
	v_and_b32_e32 v73, 0xffff0000, v47
	v_and_b32_e32 v72, 0xffff0000, v23
	v_pk_fma_f32 v[20:21], v[80:81], v[80:81], v[20:21]
	v_add_f32_e32 v24, v28, v24
	v_pk_fma_f32 v[20:21], v[72:73], v[72:73], v[20:21]
	v_and_b32_e32 v65, 0xffff0000, v52
	v_add_f32_e32 v20, v24, v20
	v_and_b32_e32 v64, 0xffff0000, v48
	v_add_f32_e32 v22, v20, v21
	v_lshlrev_b32_e32 v69, 16, v52
	v_lshlrev_b32_e32 v68, 16, v48
	v_pk_mul_f32 v[20:21], v[64:65], v[64:65]
	v_lshlrev_b32_e32 v61, 16, v53
	v_lshlrev_b32_e32 v60, 16, v49
	v_pk_fma_f32 v[20:21], v[68:69], v[68:69], v[20:21]
	v_and_b32_e32 v59, 0xffff0000, v53
	v_and_b32_e32 v58, 0xffff0000, v49
	v_pk_fma_f32 v[20:21], v[60:61], v[60:61], v[20:21]
	v_lshlrev_b32_e32 v71, 16, v54
	v_lshlrev_b32_e32 v70, 16, v50
	v_pk_fma_f32 v[20:21], v[58:59], v[58:59], v[20:21]
	v_and_b32_e32 v67, 0xffff0000, v54
	v_and_b32_e32 v66, 0xffff0000, v50
	v_pk_fma_f32 v[20:21], v[70:71], v[70:71], v[20:21]
	v_lshlrev_b32_e32 v63, 16, v55
	v_lshlrev_b32_e32 v62, 16, v51
	v_pk_fma_f32 v[20:21], v[66:67], v[66:67], v[20:21]
	v_and_b32_e32 v57, 0xffff0000, v55
	v_and_b32_e32 v56, 0xffff0000, v51
	v_pk_fma_f32 v[20:21], v[62:63], v[62:63], v[20:21]
	v_and_b32_e32 v45, 0xffff0000, v112
	v_pk_fma_f32 v[20:21], v[56:57], v[56:57], v[20:21]
	v_and_b32_e32 v44, 0xffff0000, v108
	v_add_f32_e32 v20, v22, v20
	v_add_f32_e32 v22, v20, v21
	v_lshlrev_b32_e32 v49, 16, v112
	v_lshlrev_b32_e32 v48, 16, v108
	v_pk_mul_f32 v[20:21], v[44:45], v[44:45]
	v_lshlrev_b32_e32 v31, 16, v113
	v_lshlrev_b32_e32 v30, 16, v109
	v_pk_fma_f32 v[20:21], v[48:49], v[48:49], v[20:21]
	v_and_b32_e32 v29, 0xffff0000, v113
	v_and_b32_e32 v28, 0xffff0000, v109
	v_pk_fma_f32 v[20:21], v[30:31], v[30:31], v[20:21]
	v_lshlrev_b32_e32 v55, 16, v114
	v_lshlrev_b32_e32 v54, 16, v110
	v_pk_fma_f32 v[20:21], v[28:29], v[28:29], v[20:21]
	v_and_b32_e32 v53, 0xffff0000, v114
	v_and_b32_e32 v52, 0xffff0000, v110
	v_pk_fma_f32 v[20:21], v[54:55], v[54:55], v[20:21]
	v_lshlrev_b32_e32 v51, 16, v115
	v_lshlrev_b32_e32 v50, 16, v111
	v_pk_fma_f32 v[20:21], v[52:53], v[52:53], v[20:21]
	v_and_b32_e32 v47, 0xffff0000, v115
	v_and_b32_e32 v46, 0xffff0000, v111
	v_pk_fma_f32 v[20:21], v[50:51], v[50:51], v[20:21]
	s_nop 0
	v_pk_fma_f32 v[20:21], v[46:47], v[46:47], v[20:21]
	s_nop 0
	v_add_f32_e32 v20, v22, v20
	v_add_f32_e32 v20, v20, v21
	v_mov_b32_e32 v21, v20
	s_nop 1
	v_permlane32_swap_b32_e32 v20, v21
	v_add_f32_e32 v20, v20, v21
	v_fmamk_f32 v20, v20, 0x3c000000, v1
	v_cmp_gt_f32_e32 vcc, s33, v20
	v_mul_f32_e32 v21, 0x4b800000, v20
	s_nop 0
	v_cndmask_b32_e32 v20, v20, v21, vcc
	v_rsq_f32_e32 v20, v20
	s_nop 0
	v_mul_f32_e32 v21, 0x45800000, v20
	v_cndmask_b32_e32 v20, v20, v21, vcc
	v_mul_f32_e32 v91, 0x3dd53b94, v20
	ds_read_b128 v[20:23], v248 offset:16
	ds_read_b128 v[24:27], v248
	s_waitcnt lgkmcnt(0)
	v_mul_f32_e32 v20, v20, v91
	v_mul_f32_e32 v24, v24, v91
	v_mul_f32_e32 v25, v25, v91
	v_mul_f32_e32 v21, v21, v91
	v_mul_f32_e32 v26, v26, v91
	v_mul_f32_e32 v22, v22, v91
	v_mul_f32_e32 v27, v27, v91
	v_mul_f32_e32 v23, v23, v91
	v_mul_f32_e32 v24, v24, v106
	v_mul_f32_e32 v20, v20, v107
	v_mul_f32_e32 v25, v25, v104
	v_mul_f32_e32 v21, v21, v105
	v_mul_f32_e32 v26, v26, v101
	v_mul_f32_e32 v22, v22, v103
	v_mul_f32_e32 v27, v27, v97
	v_mul_f32_e32 v23, v23, v99
	v_cvt_pk_bf16_f32 v114, v24, v25
	v_cvt_pk_bf16_f32 v115, v26, v27
	v_cvt_pk_bf16_f32 v116, v20, v21
	v_cvt_pk_bf16_f32 v117, v22, v23
	ds_read_b128 v[20:23], v248 offset:80
	ds_read_b128 v[24:27], v248 offset:64
	v_and_b32_e32 v101, 0xffff0000, v8
	v_mov_b32_e32 v103, v101
	v_lshlrev_b32_e32 v97, 16, v9
	v_and_b32_e32 v99, 0xffff0000, v9
	s_waitcnt lgkmcnt(0)
; __device__ __forceinline__ u32x4 pack8(const float* f) { u32x4 w; w.x = cvtpk(f[0], f[1]); w.y = cvtpk(f[2], f[3]); w.z = cvtpk(f[4], f[5]); w.w = cvtpk(f[6], f[7]); return w; }
; __device__ __forceinline__ bf16x8 pack8(const f32x4& a, const f32x4& b) { u32x4 w; w.x = cpk(a.x, a.y); w.y = cpk(a.z, a.w); w.z = cpk(b.x, b.y); w.w = cpk(b.z, b.w); return __builtin_bit_cast(bf16x8, w); }
; template <int VAR>
; __device__ __forceinline__ void attn_unit(const AUnit& u, LAS char* lds) {
;     ...
; #pragma unroll
;         for (int d0 = 0; d0 < 8; ++d0) { float f[8]; unpack8(__builtin_bit_cast(u32x4, qr[d0]), f);
;             const f32x4 g0 = *(const f32x4*)(u.gqn + d0 * 16 + hi * 8), g1 = *(const f32x4*)(u.gqn + d0 * 16 + hi * 8 + 4);
; #pragma unroll
;             for (int e = 0; e < 4; ++e) { f[e] *= rn * g0[e]; f[4 + e] *= rn * g1[e]; }
;             qr[d0] = __builtin_bit_cast(bf16x8, pack8(f)); }
;         const int pos = u.pos0 + wq * 32 + r32;
; #pragma unroll
;         for (int a = 0; a < 2; ++a) { float x1[8], x2[8]; unpack8(__builtin_bit_cast(u32x4, qr[8 + a]), x1); unpack8(__builtin_bit_cast(u32x4, qr[10 + a]), x2);
;             const int i0 = a * 16 + hi * 8;
;             const f32x4 ga0 = *(const f32x4*)(u.gqr + i0), ga1 = *(const f32x4*)(u.gqr + i0 + 4), gb0 = *(const f32x4*)(u.gqr + 32 + i0), gb1 = *(const f32x4*)(u.gqr + 32 + i0 + 4);
	v_mul_f32_e32 v20, v20, v91
	v_mul_f32_e32 v24, v24, v91
	v_mul_f32_e32 v25, v25, v91
	v_mul_f32_e32 v21, v21, v91
	v_mul_f32_e32 v26, v26, v91
	v_mul_f32_e32 v22, v22, v91
	v_mul_f32_e32 v27, v27, v91
	v_mul_f32_e32 v23, v23, v91
	v_mul_f32_e32 v24, v24, v100
	v_mul_f32_e32 v20, v20, v102
	v_mul_f32_e32 v25, v25, v96
	v_mul_f32_e32 v21, v21, v98
	v_mul_f32_e32 v26, v26, v94
	v_mul_f32_e32 v22, v22, v95
	v_mul_f32_e32 v27, v27, v92
	v_mul_f32_e32 v23, v23, v93
	v_cvt_pk_bf16_f32 v118, v24, v25
	v_cvt_pk_bf16_f32 v119, v26, v27
	v_cvt_pk_bf16_f32 v120, v20, v21
	v_cvt_pk_bf16_f32 v121, v22, v23
	ds_read_b128 v[20:23], v248 offset:144
	ds_read_b128 v[24:27], v248 offset:128
	v_and_b32_e32 v100, 0xffff0000, v4
	v_lshlrev_b32_e32 v96, 16, v5
	v_and_b32_e32 v98, 0xffff0000, v5
	v_lshlrev_b32_e32 v92, 16, v6
	v_and_b32_e32 v94, 0xffff0000, v6
	v_mov_b32_e32 v9, v92
	v_lshlrev_b32_e32 v93, 16, v10
	v_and_b32_e32 v95, 0xffff0000, v10
	s_waitcnt lgkmcnt(0)
	v_mul_f32_e32 v20, v91, v20
	v_mul_f32_e32 v24, v91, v24
	v_mul_f32_e32 v25, v91, v25
	v_mul_f32_e32 v21, v91, v21
	v_mul_f32_e32 v26, v91, v26
	v_mul_f32_e32 v22, v91, v22
	v_mul_f32_e32 v27, v91, v27
	v_mul_f32_e32 v23, v91, v23
	v_mul_f32_e32 v24, v24, v82
	v_mul_f32_e32 v20, v20, v86
	v_mul_f32_e32 v25, v25, v78
	v_mul_f32_e32 v21, v21, v84
	v_mul_f32_e32 v26, v26, v76
	v_mul_f32_e32 v22, v22, v80
	v_mul_f32_e32 v27, v27, v74
	v_mul_f32_e32 v23, v23, v72
	v_cvt_pk_bf16_f32 v122, v24, v25
	v_cvt_pk_bf16_f32 v123, v26, v27
	v_cvt_pk_bf16_f32 v124, v20, v21
	v_cvt_pk_bf16_f32 v125, v22, v23
	ds_read_b128 v[20:23], v248 offset:208
	ds_read_b128 v[24:27], v248 offset:192
	v_lshlrev_b32_e32 v80, 16, v12
	v_and_b32_e32 v12, 0xffff0000, v12
	v_and_b32_e32 v78, 0xffff0000, v13
	v_lshlrev_b32_e32 v72, 16, v14
	v_and_b32_e32 v14, 0xffff0000, v14
	v_lshlrev_b32_e32 v84, 16, v7
	v_mov_b32_e32 v10, v14
	v_and_b32_e32 v86, 0xffff0000, v7
	v_mov_b32_e32 v5, v84
	v_mov_b32_e32 v7, v86
	s_waitcnt lgkmcnt(0)
	v_mul_f32_e32 v20, v91, v20
	v_mul_f32_e32 v24, v91, v24
	v_mul_f32_e32 v25, v91, v25
	v_mul_f32_e32 v21, v91, v21
	v_mul_f32_e32 v26, v91, v26
	v_mul_f32_e32 v22, v91, v22
	v_mul_f32_e32 v27, v91, v27
	v_mul_f32_e32 v23, v91, v23
	v_mul_f32_e32 v24, v24, v83
	v_mul_f32_e32 v20, v20, v87
	v_mul_f32_e32 v25, v25, v79
	v_mul_f32_e32 v21, v21, v85
	v_mul_f32_e32 v26, v26, v77
	v_mul_f32_e32 v22, v22, v81
	v_mul_f32_e32 v27, v27, v75
	v_mul_f32_e32 v23, v23, v73
	v_cvt_pk_bf16_f32 v126, v24, v25
	v_cvt_pk_bf16_f32 v127, v26, v27
	v_cvt_pk_bf16_f32 v128, v20, v21
	v_cvt_pk_bf16_f32 v129, v22, v23
	ds_read_b128 v[20:23], v248 offset:272
	ds_read_b128 v[24:27], v248 offset:256
	v_lshlrev_b32_e32 v73, 16, v18
	v_lshlrev_b32_e32 v81, 16, v16
	v_and_b32_e32 v79, 0xffff0000, v17
	v_lshlrev_b32_e32 v85, 16, v11
	v_and_b32_e32 v87, 0xffff0000, v11
	v_mov_b32_e32 v11, v94
	s_waitcnt lgkmcnt(0)
	v_mul_f32_e32 v20, v91, v20
	v_mul_f32_e32 v24, v91, v24
	v_mul_f32_e32 v25, v91, v25
	v_mul_f32_e32 v21, v91, v21
	v_mul_f32_e32 v26, v91, v26
	v_mul_f32_e32 v22, v91, v22
	v_mul_f32_e32 v27, v91, v27
	v_mul_f32_e32 v23, v91, v23
	v_mul_f32_e32 v24, v24, v68
	v_mul_f32_e32 v20, v20, v70
	v_mul_f32_e32 v25, v25, v64
	v_mul_f32_e32 v21, v21, v66
	v_mul_f32_e32 v26, v26, v60
	v_mul_f32_e32 v22, v22, v62
	v_mul_f32_e32 v27, v27, v58
	v_mul_f32_e32 v23, v23, v56
	v_cvt_pk_bf16_f32 v130, v24, v25
	v_cvt_pk_bf16_f32 v131, v26, v27
	v_cvt_pk_bf16_f32 v132, v20, v21
	v_cvt_pk_bf16_f32 v133, v22, v23
	ds_read_b128 v[20:23], v248 offset:336
	ds_read_b128 v[24:27], v248 offset:320
	v_lshl_or_b32 v64, v182, 3, v43
	v_lshlrev_b32_e32 v66, 16, v15
	v_and_b32_e32 v70, 0xffff0000, v15
	v_and_b32_e32 v15, 0xffff0000, v18
	v_lshlrev_b32_e32 v18, 16, v13
	v_and_b32_e32 v13, 0xffff0000, v16
	v_or_b32_e32 v16, 16, v64
	v_mov_b32_e32 v102, v13
	v_pk_mul_f32 v[102:103], v[102:103], v[102:103]
	v_mov_b32_e32 v6, v70
	s_waitcnt lgkmcnt(0)
	v_mul_f32_e32 v20, v91, v20
	v_mul_f32_e32 v24, v91, v24
	v_mul_f32_e32 v25, v91, v25
	v_mul_f32_e32 v21, v91, v21
	v_mul_f32_e32 v26, v91, v26
	v_mul_f32_e32 v22, v91, v22
	v_mul_f32_e32 v27, v91, v27
	v_mul_f32_e32 v23, v91, v23
	v_mul_f32_e32 v24, v24, v69
	v_mul_f32_e32 v20, v20, v71
	v_mul_f32_e32 v25, v25, v65
	v_mul_f32_e32 v21, v21, v67
	v_mul_f32_e32 v26, v26, v61
	v_mul_f32_e32 v22, v22, v63
	v_mul_f32_e32 v27, v27, v59
	v_mul_f32_e32 v23, v23, v57
	v_cvt_pk_bf16_f32 v134, v24, v25
	v_cvt_pk_bf16_f32 v135, v26, v27
	v_cvt_pk_bf16_f32 v136, v20, v21
	v_cvt_pk_bf16_f32 v137, v22, v23
	ds_read_b128 v[20:23], v248 offset:400
	ds_read_b128 v[24:27], v248 offset:384
	v_ashrrev_i32_e32 v65, 31, v64
	v_lshl_add_u64 v[60:61], v[64:65], 3, s[6:7]
	v_lshlrev_b32_e32 v67, 16, v19
	v_and_b32_e32 v71, 0xffff0000, v19
	v_lshlrev_b32_e32 v19, 16, v17
	v_ashrrev_i32_e32 v17, 31, v16
	v_lshl_add_u64 v[64:65], v[16:17], 3, s[6:7]
	v_mov_b32_e32 v16, v18
	v_mov_b32_e32 v17, v96
	s_waitcnt lgkmcnt(0)
	v_mul_f32_e32 v20, v91, v20
	v_mul_f32_e32 v24, v91, v24
	v_mul_f32_e32 v25, v91, v25
	v_mul_f32_e32 v21, v91, v21
	v_mul_f32_e32 v26, v91, v26
	v_mul_f32_e32 v22, v91, v22
	v_mul_f32_e32 v27, v91, v27
	v_mul_f32_e32 v23, v91, v23
	v_mul_f32_e32 v24, v24, v48
	v_mul_f32_e32 v20, v20, v54
	v_mul_f32_e32 v25, v25, v44
	v_mul_f32_e32 v21, v21, v52
	v_mul_f32_e32 v26, v26, v30
	v_mul_f32_e32 v22, v22, v50
	v_mul_f32_e32 v27, v27, v28
	v_mul_f32_e32 v23, v23, v46
	v_cvt_pk_bf16_f32 v138, v24, v25
	v_cvt_pk_bf16_f32 v139, v26, v27
	v_cvt_pk_bf16_f32 v140, v20, v21
	v_cvt_pk_bf16_f32 v141, v22, v23
	ds_read_b128 v[20:23], v248 offset:464
	ds_read_b128 v[24:27], v248 offset:448
	s_waitcnt lgkmcnt(0)
; __device__ __forceinline__ u32x4 pack8(const float* f) { u32x4 w; w.x = cvtpk(f[0], f[1]); w.y = cvtpk(f[2], f[3]); w.z = cvtpk(f[4], f[5]); w.w = cvtpk(f[6], f[7]); return w; }
; __device__ __forceinline__ bf16x8 pack8(const f32x4& a, const f32x4& b) { u32x4 w; w.x = cpk(a.x, a.y); w.y = cpk(a.z, a.w); w.z = cpk(b.x, b.y); w.w = cpk(b.z, b.w); return __builtin_bit_cast(bf16x8, w); }
; template <int VAR>
; __device__ __forceinline__ void attn_unit(const AUnit& u, LAS char* lds) {
;     ...
;         { auto rr = __builtin_amdgcn_permlane32_swap(__float_as_uint(ssn), __float_as_uint(ssn), false, false); ssn = __uint_as_float(rr[0]) + __uint_as_float(rr[1]); }
;         { auto rr = __builtin_amdgcn_permlane32_swap(__float_as_uint(ssr), __float_as_uint(ssr), false, false); ssr = __uint_as_float(rr[0]) + __uint_as_float(rr[1]); }
;         const float rn = rsqrtf(ssn * (1.f / 128) + NORM_EPS) * QSCALE, rr_ = rsqrtf(ssr * (1.f / ROPE) + NORM_EPS);
; #pragma unroll
;         for (int d0 = 0; d0 < 8; ++d0) { float f[8]; unpack8(__builtin_bit_cast(u32x4, qr[d0]), f);
;             const f32x4 g0 = *(const f32x4*)(u.gqn + d0 * 16 + hi * 8), g1 = *(const f32x4*)(u.gqn + d0 * 16 + hi * 8 + 4);
; #pragma unroll
;             for (int e = 0; e < 4; ++e) { f[e] *= rn * g0[e]; f[4 + e] *= rn * g1[e]; }
;             qr[d0] = __builtin_bit_cast(bf16x8, pack8(f)); }
;         const int pos = u.pos0 + wq * 32 + r32;
; #pragma unroll
;         for (int a = 0; a < 2; ++a) { float x1[8], x2[8]; unpack8(__builtin_bit_cast(u32x4, qr[8 + a]), x1); unpack8(__builtin_bit_cast(u32x4, qr[10 + a]), x2);
;             const int i0 = a * 16 + hi * 8;
;             const f32x4 ga0 = *(const f32x4*)(u.gqr + i0), ga1 = *(const f32x4*)(u.gqr + i0 + 4), gb0 = *(const f32x4*)(u.gqr + 32 + i0), gb1 = *(const f32x4*)(u.gqr + 32 + i0 + 4);
;             float y1[8], y2[8];
; #pragma unroll
;             for (int e = 0; e < 8; ++e) { const float v1 = x1[e] * rr_ * (e < 4 ? ga0[e & 3] : ga1[e & 3]), v2 = x2[e] * rr_ * (e < 4 ? gb0[e & 3] : gb1[e & 3]);
;                 const float2 cs = u.tab[pos * 32 + i0 + e];
;                 y1[e] = (v1 * cs.x - v2 * cs.y) * QSCALE; y2[e] = (v2 * cs.x + v1 * cs.y) * QSCALE; }
;             qr[8 + a] = __builtin_bit_cast(bf16x8, pack8(y1)); qr[10 + a] = __builtin_bit_cast(bf16x8, pack8(y2)); }
	v_mul_f32_e32 v20, v91, v20
	v_mul_f32_e32 v24, v91, v24
	v_mul_f32_e32 v25, v91, v25
	v_mul_f32_e32 v21, v91, v21
	v_mul_f32_e32 v26, v91, v26
	v_mul_f32_e32 v22, v91, v22
	v_mul_f32_e32 v27, v91, v27
	v_mul_f32_e32 v23, v91, v23
	v_mul_f32_e32 v24, v24, v49
	v_mul_f32_e32 v20, v20, v55
	v_mul_f32_e32 v25, v25, v45
	v_mul_f32_e32 v21, v21, v53
	v_mul_f32_e32 v26, v26, v31
	v_mul_f32_e32 v22, v22, v51
	v_mul_f32_e32 v27, v27, v29
	v_mul_f32_e32 v23, v23, v47
	v_cvt_pk_bf16_f32 v142, v24, v25
	v_cvt_pk_bf16_f32 v143, v26, v27
	v_cvt_pk_bf16_f32 v144, v20, v21
	v_cvt_pk_bf16_f32 v145, v22, v23
	ds_read_b128 v[20:23], v248 offset:512
	ds_read_b128 v[24:27], v248 offset:528
	ds_read_b128 v[28:31], v248 offset:640
	ds_read_b128 v[44:47], v248 offset:656
	v_mov_b64_e32 v[48:49], v[228:229]
	v_mov_b64_e32 v[50:51], v[230:231]
	v_mov_b64_e32 v[52:53], v[232:233]
	v_mov_b64_e32 v[54:55], v[234:235]
	v_mov_b64_e32 v[56:57], v[240:241]
	v_mov_b64_e32 v[58:59], v[242:243]
	v_mov_b64_e32 v[60:61], v[244:245]
	v_mov_b64_e32 v[62:63], v[246:247]
	global_load_dwordx4 v[228:231], v[64:65], off offset:48
	global_load_dwordx4 v[232:235], v[64:65], off offset:32
	global_load_dwordx4 v[240:243], v[64:65], off offset:16
	global_load_dwordx4 v[244:247], v[64:65], off
	s_waitcnt lgkmcnt(0)
	v_mov_b32_e32 v82, v20
	v_mov_b32_e32 v68, v26
	v_lshlrev_b32_e32 v20, 16, v4
	v_mov_b32_e32 v69, v46
	v_mov_b32_e32 v46, v27
	v_mov_b32_e32 v26, v12
	v_mov_b32_e32 v27, v100
	v_mov_b32_e32 v74, v24
	v_mov_b32_e32 v75, v44
	v_mov_b32_e32 v44, v25
	v_mov_b32_e32 v24, v80
	v_mov_b32_e32 v25, v20
	v_pk_mul_f32 v[26:27], v[26:27], v[26:27]
	v_mov_b32_e32 v83, v28
	v_mov_b32_e32 v28, v21
	v_lshlrev_b32_e32 v21, 16, v8
	v_pk_fma_f32 v[24:25], v[24:25], v[24:25], v[26:27]
	v_mov_b32_e32 v76, v22
	v_mov_b32_e32 v77, v30
	v_mov_b32_e32 v30, v23
	v_mov_b32_e32 v22, v78
	v_mov_b32_e32 v23, v98
	v_pk_fma_f32 v[16:17], v[16:17], v[16:17], v[24:25]
	v_mov_b32_e32 v26, v81
	v_mov_b32_e32 v27, v21
	v_mov_b32_e32 v8, v72
	v_pk_fma_f32 v[16:17], v[22:23], v[22:23], v[16:17]
	v_mov_b32_e32 v22, v19
	v_mov_b32_e32 v23, v97
	v_pk_fma_f32 v[26:27], v[26:27], v[26:27], v[102:103]
	v_pk_fma_f32 v[8:9], v[8:9], v[8:9], v[16:17]
	v_mov_b32_e32 v24, v79
	v_mov_b32_e32 v25, v99
	v_pk_fma_f32 v[22:23], v[22:23], v[22:23], v[26:27]
	v_mov_b32_e32 v4, v66
	v_pk_fma_f32 v[8:9], v[10:11], v[10:11], v[8:9]
	v_mov_b32_e32 v10, v73
	v_mov_b32_e32 v11, v93
	v_pk_fma_f32 v[22:23], v[24:25], v[24:25], v[22:23]
	v_pk_fma_f32 v[4:5], v[4:5], v[4:5], v[8:9]
	v_mov_b32_e32 v16, v15
	v_mov_b32_e32 v17, v95
	v_pk_fma_f32 v[10:11], v[10:11], v[10:11], v[22:23]
	v_pk_fma_f32 v[4:5], v[6:7], v[6:7], v[4:5]
	v_mov_b32_e32 v6, v67
	v_mov_b32_e32 v7, v85
	v_pk_fma_f32 v[10:11], v[16:17], v[16:17], v[10:11]
	v_mov_b32_e32 v8, v71
	v_mov_b32_e32 v9, v87
	v_pk_fma_f32 v[6:7], v[6:7], v[6:7], v[10:11]
	v_pk_add_f32 v[4:5], v[4:5], v[4:5] op_sel:[0,1] op_sel_hi:[1,0]
	v_pk_fma_f32 v[6:7], v[8:9], v[8:9], v[6:7]
	s_nop 0
	v_pk_add_f32 v[4:5], v[4:5], v[6:7]
	s_nop 0
	v_pk_add_f32 v[4:5], v[4:5], v[6:7] op_sel:[0,1] op_sel_hi:[1,0]
	s_nop 0
	v_mov_b32_e32 v5, v4
	s_nop 1
	v_permlane32_swap_b32_e32 v4, v5
	v_add_f32_e32 v4, v4, v5
	v_fmamk_f32 v4, v4, 0x3c800000, v1
	v_cmp_gt_f32_e32 vcc, s33, v4
	v_mul_f32_e32 v5, 0x4b800000, v4
	s_nop 0
	v_cndmask_b32_e32 v4, v4, v5, vcc
	v_rsq_f32_e32 v4, v4
	s_nop 0
	v_mul_f32_e32 v5, 0x45800000, v4
	v_cndmask_b32_e32 v102, v4, v5, vcc
	v_pk_mul_f32 v[4:5], v[102:103], v[80:81] op_sel_hi:[0,1]
	v_pk_mul_f32 v[4:5], v[4:5], v[82:83]
	v_pk_mul_f32 v[20:21], v[102:103], v[20:21] op_sel_hi:[0,1]
	v_pk_mul_f32 v[6:7], v[4:5], v[60:61]
	v_pk_mul_f32 v[4:5], v[4:5], v[60:61] op_sel:[1,0] op_sel_hi:[0,1]
	v_add_f32_e32 v4, v4, v5
	v_mul_f32_e32 v9, 0x3dd53b94, v4
	v_pk_mul_f32 v[4:5], v[102:103], v[12:13] op_sel_hi:[0,1]
	v_sub_f32_e32 v6, v6, v7
	v_pk_mul_f32 v[4:5], v[4:5], v[28:29]
	v_mul_f32_e32 v8, 0x3dd53b94, v6
	v_pk_mul_f32 v[6:7], v[4:5], v[62:63]
	v_pk_mul_f32 v[4:5], v[4:5], v[62:63] op_sel:[1,0] op_sel_hi:[0,1]
	v_add_f32_e32 v4, v4, v5
	v_mul_f32_e32 v11, 0x3dd53b94, v4
	v_pk_mul_f32 v[4:5], v[102:103], v[18:19] op_sel_hi:[0,1]
	v_sub_f32_e32 v6, v6, v7
	v_pk_mul_f32 v[4:5], v[4:5], v[76:77]
	v_mul_f32_e32 v10, 0x3dd53b94, v6
	v_pk_mul_f32 v[6:7], v[4:5], v[56:57]
	v_pk_mul_f32 v[4:5], v[4:5], v[56:57] op_sel:[1,0] op_sel_hi:[0,1]
	v_add_f32_e32 v4, v4, v5
	v_mul_f32_e32 v13, 0x3dd53b94, v4
	v_pk_mul_f32 v[4:5], v[102:103], v[78:79] op_sel_hi:[0,1]
	v_sub_f32_e32 v6, v6, v7
	v_pk_mul_f32 v[4:5], v[4:5], v[30:31]
	v_mul_f32_e32 v12, 0x3dd53b94, v6
	v_pk_mul_f32 v[6:7], v[4:5], v[58:59]
	v_pk_mul_f32 v[4:5], v[4:5], v[58:59] op_sel:[1,0] op_sel_hi:[0,1]
	v_add_f32_e32 v4, v4, v5
	v_mul_f32_e32 v17, 0x3dd53b94, v4
	v_pk_mul_f32 v[4:5], v[102:103], v[72:73] op_sel_hi:[0,1]
	v_sub_f32_e32 v6, v6, v7
	v_pk_mul_f32 v[4:5], v[4:5], v[74:75]
	v_mul_f32_e32 v16, 0x3dd53b94, v6
	v_pk_mul_f32 v[6:7], v[4:5], v[52:53]
	v_pk_mul_f32 v[4:5], v[4:5], v[52:53] op_sel:[1,0] op_sel_hi:[0,1]
	v_add_f32_e32 v4, v4, v5
	v_mul_f32_e32 v19, 0x3dd53b94, v4
	v_pk_mul_f32 v[4:5], v[102:103], v[14:15] op_sel_hi:[0,1]
	v_sub_f32_e32 v6, v6, v7
	v_pk_mul_f32 v[4:5], v[4:5], v[44:45]
	v_mul_f32_e32 v18, 0x3dd53b94, v6
	v_pk_mul_f32 v[6:7], v[4:5], v[54:55]
	v_pk_mul_f32 v[4:5], v[4:5], v[54:55] op_sel:[1,0] op_sel_hi:[0,1]
	v_add_f32_e32 v4, v4, v5
	v_mul_f32_e32 v15, 0x3dd53b94, v4
	v_pk_mul_f32 v[4:5], v[102:103], v[66:67] op_sel_hi:[0,1]
	v_sub_f32_e32 v6, v6, v7
	v_pk_mul_f32 v[4:5], v[4:5], v[68:69]
	v_mul_f32_e32 v14, 0x3dd53b94, v6
	v_pk_mul_f32 v[6:7], v[4:5], v[48:49]
	v_pk_mul_f32 v[4:5], v[4:5], v[48:49] op_sel:[1,0] op_sel_hi:[0,1]
	v_add_f32_e32 v4, v4, v5
	v_mul_f32_e32 v23, 0x3dd53b94, v4
	v_pk_mul_f32 v[4:5], v[102:103], v[70:71] op_sel_hi:[0,1]
	v_sub_f32_e32 v6, v6, v7
	v_pk_mul_f32 v[4:5], v[4:5], v[46:47]
	v_mul_f32_e32 v22, 0x3dd53b94, v6
	v_pk_mul_f32 v[6:7], v[4:5], v[50:51]
	v_pk_mul_f32 v[4:5], v[4:5], v[50:51] op_sel:[1,0] op_sel_hi:[0,1]
	v_sub_f32_e32 v6, v6, v7
	v_add_f32_e32 v4, v4, v5
	v_mul_f32_e32 v6, 0x3dd53b94, v6
	v_mul_f32_e32 v4, 0x3dd53b94, v4
	v_cvt_pk_bf16_f32 v146, v8, v10
	v_cvt_pk_bf16_f32 v147, v12, v16
	v_cvt_pk_bf16_f32 v148, v18, v14
	v_cvt_pk_bf16_f32 v149, v22, v6
	v_cvt_pk_bf16_f32 v150, v9, v11
	v_cvt_pk_bf16_f32 v151, v13, v17
	v_cvt_pk_bf16_f32 v152, v19, v15
	v_cvt_pk_bf16_f32 v153, v23, v4
	ds_read_b128 v[4:7], v248 offset:592
	ds_read_b128 v[8:11], v248 offset:576
	ds_read_b128 v[12:15], v248 offset:720
	ds_read_b128 v[16:19], v248 offset:704
	s_waitcnt lgkmcnt(0)
; #define LAS __attribute__((address_space(3)))
; __device__ __forceinline__ u32x4 pack8(const float* f) { u32x4 w; w.x = cvtpk(f[0], f[1]); w.y = cvtpk(f[2], f[3]); w.z = cvtpk(f[4], f[5]); w.w = cvtpk(f[6], f[7]); return w; }
; __device__ __forceinline__ int v_rd_base(int lane) { return ((lane & 3) << 3) | (((lane >> 2) & 3) << 6) | (((lane >> 4) & 1) << 5) | (((lane >> 5) & 1) << 8); }
; #define AWAITV() asm volatile("s_waitcnt vmcnt(0)" ::: "memory")
; __device__ __forceinline__ bf16x8 pack8(const f32x4& a, const f32x4& b) { u32x4 w; w.x = cpk(a.x, a.y); w.y = cpk(a.z, a.w); w.z = cpk(b.x, b.y); w.w = cpk(b.z, b.w); return __builtin_bit_cast(bf16x8, w); }
; template <int VAR>
; __device__ __forceinline__ void attn_unit(const AUnit& u, LAS char* lds) {
;     ...
;         for (int a = 0; a < 2; ++a) { float x1[8], x2[8]; unpack8(__builtin_bit_cast(u32x4, qr[8 + a]), x1); unpack8(__builtin_bit_cast(u32x4, qr[10 + a]), x2);
;             const int i0 = a * 16 + hi * 8;
;             const f32x4 ga0 = *(const f32x4*)(u.gqr + i0), ga1 = *(const f32x4*)(u.gqr + i0 + 4), gb0 = *(const f32x4*)(u.gqr + 32 + i0), gb1 = *(const f32x4*)(u.gqr + 32 + i0 + 4);
;             float y1[8], y2[8];
; #pragma unroll
;             for (int e = 0; e < 8; ++e) { const float v1 = x1[e] * rr_ * (e < 4 ? ga0[e & 3] : ga1[e & 3]), v2 = x2[e] * rr_ * (e < 4 ? gb0[e & 3] : gb1[e & 3]);
;                 const float2 cs = u.tab[pos * 32 + i0 + e];
;                 y1[e] = (v1 * cs.x - v2 * cs.y) * QSCALE; y2[e] = (v2 * cs.x + v1 * cs.y) * QSCALE; }
;             qr[8 + a] = __builtin_bit_cast(bf16x8, pack8(y1)); qr[10 + a] = __builtin_bit_cast(bf16x8, pack8(y2)); }
;     }
;     float m_reg = -1e30f, l_reg = 0.f; f32x16 o[4]; o[0] = f32x16{}; o[1] = f32x16{}; o[2] = f32x16{}; o[3] = f32x16{};
;     LAS float* wsf = (LAS float*)(lds + OFF_WS) + wid * 64; LAS float* li_l = wsf; LAS float* al_l = wsf + 32;
;     const int vb0 = (int)(unsigned)(uintptr_t)lds + v_rd_base(lane);
;     AWAITV();
;     __syncthreads();
	v_mov_b32_e32 v22, v8
	v_mov_b32_e32 v23, v16
	v_pk_mul_f32 v[48:49], v[20:21], v[22:23]
	s_waitcnt vmcnt(0)
	v_mov_b64_e32 v[20:21], v[228:229]
	v_mov_b64_e32 v[22:23], v[230:231]
	v_mov_b64_e32 v[24:25], v[232:233]
	v_mov_b64_e32 v[26:27], v[234:235]
	v_mov_b64_e32 v[28:29], v[240:241]
	v_mov_b64_e32 v[30:31], v[242:243]
	v_mov_b64_e32 v[44:45], v[244:245]
	v_mov_b64_e32 v[46:47], v[246:247]
	v_mov_b32_e32 v16, v9
	s_waitcnt vmcnt(0)
	v_pk_mul_f32 v[50:51], v[48:49], v[44:45]
	s_nop 0
	v_sub_f32_e32 v8, v50, v51
	v_pk_mul_f32 v[44:45], v[48:49], v[44:45] op_sel:[1,0] op_sel_hi:[0,1]
	v_mul_f32_e32 v43, 0x3dd53b94, v8
	v_add_f32_e32 v8, v44, v45
	v_pk_mul_f32 v[44:45], v[102:103], v[100:101] op_sel_hi:[0,1]
	v_mul_f32_e32 v48, 0x3dd53b94, v8
	v_pk_mul_f32 v[8:9], v[44:45], v[16:17]
	s_nop 0
	v_pk_mul_f32 v[16:17], v[8:9], v[46:47]
	v_pk_mul_f32 v[8:9], v[8:9], v[46:47] op_sel:[1,0] op_sel_hi:[0,1]
	v_sub_f32_e32 v16, v16, v17
	v_add_f32_e32 v8, v8, v9
	v_mul_f32_e32 v44, 0x3dd53b94, v16
	v_mul_f32_e32 v45, 0x3dd53b94, v8
	v_pk_mul_f32 v[8:9], v[102:103], v[96:97] op_sel_hi:[0,1]
	v_mov_b32_e32 v16, v10
	v_mov_b32_e32 v17, v18
	v_pk_mul_f32 v[8:9], v[8:9], v[16:17]
	v_mov_b32_e32 v18, v11
	v_pk_mul_f32 v[16:17], v[8:9], v[28:29]
	v_pk_mul_f32 v[8:9], v[8:9], v[28:29] op_sel:[1,0] op_sel_hi:[0,1]
	v_add_f32_e32 v8, v8, v9
	v_sub_f32_e32 v10, v16, v17
	v_mul_f32_e32 v17, 0x3dd53b94, v8
	v_pk_mul_f32 v[8:9], v[102:103], v[98:99] op_sel_hi:[0,1]
	v_pk_mul_f32 v[8:9], v[8:9], v[18:19]
	v_mul_f32_e32 v16, 0x3dd53b94, v10
	v_pk_mul_f32 v[10:11], v[8:9], v[30:31]
	v_pk_mul_f32 v[8:9], v[8:9], v[30:31] op_sel:[1,0] op_sel_hi:[0,1]
	v_sub_f32_e32 v10, v10, v11
	v_add_f32_e32 v8, v8, v9
	v_mul_f32_e32 v18, 0x3dd53b94, v10
	v_mul_f32_e32 v19, 0x3dd53b94, v8
	v_pk_mul_f32 v[8:9], v[102:103], v[92:93] op_sel_hi:[0,1]
	v_mov_b32_e32 v10, v4
	v_mov_b32_e32 v11, v12
	v_pk_mul_f32 v[8:9], v[8:9], v[10:11]
	v_mov_b32_e32 v12, v5
	v_pk_mul_f32 v[10:11], v[8:9], v[24:25]
	v_pk_mul_f32 v[8:9], v[8:9], v[24:25] op_sel:[1,0] op_sel_hi:[0,1]
	v_sub_f32_e32 v4, v10, v11
	v_mul_f32_e32 v10, 0x3dd53b94, v4
	v_add_f32_e32 v4, v8, v9
	v_pk_mul_f32 v[8:9], v[102:103], v[94:95] op_sel_hi:[0,1]
	v_mul_f32_e32 v11, 0x3dd53b94, v4
	v_pk_mul_f32 v[4:5], v[8:9], v[12:13]
	v_cvt_pk_bf16_f32 v154, v43, v44
	v_cvt_pk_bf16_f32 v155, v16, v18
	v_mov_b32_e32 v16, v3
	v_pk_mul_f32 v[8:9], v[4:5], v[26:27]
	v_pk_mul_f32 v[4:5], v[4:5], v[26:27] op_sel:[1,0] op_sel_hi:[0,1]
	v_sub_f32_e32 v8, v8, v9
	v_add_f32_e32 v4, v4, v5
	v_mul_f32_e32 v12, 0x3dd53b94, v8
	v_mul_f32_e32 v13, 0x3dd53b94, v4
	v_pk_mul_f32 v[4:5], v[102:103], v[84:85] op_sel_hi:[0,1]
	v_mov_b32_e32 v8, v6
	v_mov_b32_e32 v9, v14
	v_pk_mul_f32 v[4:5], v[4:5], v[8:9]
	v_mov_b32_e32 v14, v7
	v_pk_mul_f32 v[8:9], v[4:5], v[20:21]
	v_pk_mul_f32 v[4:5], v[4:5], v[20:21] op_sel:[1,0] op_sel_hi:[0,1]
	v_add_f32_e32 v4, v4, v5
	v_sub_f32_e32 v6, v8, v9
	v_mul_f32_e32 v9, 0x3dd53b94, v4
	v_pk_mul_f32 v[4:5], v[102:103], v[86:87] op_sel_hi:[0,1]
	v_pk_mul_f32 v[4:5], v[4:5], v[14:15]
	v_mul_f32_e32 v8, 0x3dd53b94, v6
	v_pk_mul_f32 v[6:7], v[4:5], v[22:23]
	v_pk_mul_f32 v[4:5], v[4:5], v[22:23] op_sel:[1,0] op_sel_hi:[0,1]
	v_sub_f32_e32 v6, v6, v7
	v_add_f32_e32 v4, v4, v5
	v_mul_f32_e32 v6, 0x3dd53b94, v6
	v_mul_f32_e32 v4, 0x3dd53b94, v4
	v_lshlrev_b32_e32 v5, 4, v181
	v_cvt_pk_bf16_f32 v156, v10, v12
	v_cvt_pk_bf16_f32 v157, v8, v6
	v_cvt_pk_bf16_f32 v158, v48, v45
	v_cvt_pk_bf16_f32 v159, v17, v19
	v_cvt_pk_bf16_f32 v160, v11, v13
	v_cvt_pk_bf16_f32 v161, v9, v4
	v_lshlrev_b32_e32 v4, 3, v88
	v_and_b32_e32 v6, 0xc0, v5
	v_lshlrev_b32_e32 v7, 1, v181
	v_and_or_b32 v6, v4, 24, v6
	v_and_b32_e32 v7, 32, v7
	v_and_b32_e32 v4, 0x100, v4
	v_or3_b32 v4, v6, v7, v4
	v_add_u32_e32 v163, 0, v4
	v_and_b32_e32 v4, 0xf0, v5
	v_bitop3_b32 v185, v162, v4, 32 bitop3:0x36
	v_bitop3_b32 v186, v162, v4, 64 bitop3:0x36
	v_bitop3_b32 v187, v162, v4, s24 bitop3:0x36
	v_bitop3_b32 v207, v162, v4, s23 bitop3:0x36
	v_bitop3_b32 v208, v162, v4, s25 bitop3:0x36
	v_bitop3_b32 v209, v162, v4, s14 bitop3:0x36
	v_bitop3_b32 v210, v162, v4, s15 bitop3:0x36
	v_lshlrev_b32_e32 v4, 7, v180
	v_sub_u32_e32 v211, v183, v4
	v_add_u32_e32 v224, s10, v4
	v_bitop3_b32 v4, v32, 15, v181 bitop3:0x48
	v_lshl_or_b32 v34, v4, 4, v34
	v_bitop3_b32 v4, v33, 7, v181 bitop3:0x48
	s_waitcnt vmcnt(0)
	v_bitop3_b32 v184, v162, v5, s20 bitop3:0x78
	v_and_b32_e32 v5, 0x70, v89
	v_lshl_or_b32 v38, v4, 4, v38
	v_mov_b32_e32 v17, v3
	v_bitop3_b32 v213, v162, v5, 32 bitop3:0x36
	v_bitop3_b32 v214, v162, v5, 64 bitop3:0x36
	v_bitop3_b32 v215, v162, v5, s24 bitop3:0x36
	v_lshl_add_u64 v[174:175], s[50:51], 0, v[34:35]
	v_lshl_add_u64 v[176:177], s[52:53], 0, v[38:39]
	v_mov_b32_e32 v4, v3
	v_mov_b32_e32 v5, v3
	v_mov_b32_e32 v6, v3
	v_mov_b32_e32 v7, v3
	v_mov_b32_e32 v8, v3
	v_mov_b32_e32 v9, v3
	v_mov_b32_e32 v10, v3
	v_mov_b32_e32 v11, v3
	v_mov_b32_e32 v12, v3
	v_mov_b32_e32 v13, v3
	v_mov_b32_e32 v14, v3
	v_mov_b32_e32 v15, v3
	v_mov_b64_e32 v[32:33], v[16:17]
	v_mov_b64_e32 v[48:49], v[16:17]
	v_mov_b64_e32 v[64:65], v[16:17]
	v_mov_b64_e32 v[80:81], v[16:17]
	v_add3_u32 v216, v183, v184, s22
	v_add3_u32 v217, v183, v185, s22
	v_add3_u32 v218, v183, v186, s22
	v_add3_u32 v219, v183, v187, s22
	v_add3_u32 v220, v183, v207, s22
	v_add3_u32 v221, v183, v208, s22
	v_add3_u32 v222, v183, v209, s22
	v_add3_u32 v223, v183, v210, s22
	v_mov_b64_e32 v[30:31], v[14:15]
	v_mov_b64_e32 v[28:29], v[12:13]
	v_mov_b64_e32 v[26:27], v[10:11]
	v_mov_b64_e32 v[24:25], v[8:9]
	v_mov_b64_e32 v[22:23], v[6:7]
	v_mov_b64_e32 v[20:21], v[4:5]
	v_mov_b64_e32 v[18:19], v[2:3]
	v_mov_b64_e32 v[46:47], v[14:15]
	v_mov_b64_e32 v[44:45], v[12:13]
	v_mov_b64_e32 v[42:43], v[10:11]
	v_mov_b64_e32 v[40:41], v[8:9]
	v_mov_b64_e32 v[38:39], v[6:7]
	v_mov_b64_e32 v[36:37], v[4:5]
	v_mov_b64_e32 v[34:35], v[2:3]
	v_mov_b64_e32 v[62:63], v[14:15]
	v_mov_b64_e32 v[60:61], v[12:13]
	v_mov_b64_e32 v[58:59], v[10:11]
	v_mov_b64_e32 v[56:57], v[8:9]
	v_mov_b64_e32 v[54:55], v[6:7]
	v_mov_b64_e32 v[52:53], v[4:5]
	v_mov_b64_e32 v[50:51], v[2:3]
	v_mov_b64_e32 v[78:79], v[14:15]
	v_mov_b64_e32 v[76:77], v[12:13]
	v_mov_b64_e32 v[74:75], v[10:11]
	v_mov_b64_e32 v[72:73], v[8:9]
	v_mov_b64_e32 v[70:71], v[6:7]
	v_mov_b64_e32 v[68:69], v[4:5]
	v_mov_b64_e32 v[66:67], v[2:3]
	s_waitcnt lgkmcnt(0)
	s_barrier
	v_readfirstlane_b32 s93, v181
	s_nop 3
	s_lshr_b32 s93, s93, 8
	s_cmp_eq_u32 s93, 0
	s_cbranch_scc0 .Latt_startB
